# v17 plus XCD-local barriers released on the arrival count (count >= target) instead of waiting for the last arriver to bump the generation word
# baseline (speedup 1.0000x reference)
.LBB0_453:
	s_or_b64 exec, exec, s[6:7]
	s_waitcnt lgkmcnt(0)
	v_cvt_f32_u32_e32 v3, v0
	s_waitcnt vmcnt(1)
	v_readfirstlane_b32 s4, v2
	s_mov_b64 s[6:7], -1
	v_rcp_iflag_f32_e32 v3, v3
	v_add_u32_e32 v1, s4, v1
	v_add_u32_e32 v4, 1, v1
	s_add_u32 s4, s2, 0x1000
	v_mul_f32_e32 v2, 0x4f7ffffe, v3
	v_cvt_u32_f32_e32 v2, v2
	v_sub_u32_e32 v3, 0, v0
	s_addc_u32 s5, s3, 0
	v_mul_lo_u32 v3, v3, v2
	v_mul_hi_u32 v3, v2, v3
	v_add_u32_e32 v2, v2, v3
	v_mul_hi_u32 v2, v1, v2
	v_mul_lo_u32 v3, v2, v0
	v_sub_u32_e32 v1, v1, v3
	v_add_u32_e32 v5, 1, v2
	v_cmp_ge_u32_e32 vcc, v1, v0
	v_sub_u32_e32 v3, v1, v0
	s_nop 0
	v_cndmask_b32_e32 v2, v2, v5, vcc
	v_cndmask_b32_e32 v1, v1, v3, vcc
	v_add_u32_e32 v3, 1, v2
	v_cmp_ge_u32_e32 vcc, v1, v0
	s_nop 1
	v_cndmask_b32_e32 v2, v2, v3, vcc
	v_mul_lo_u32 v1, v0, v2
	v_add_u32_e32 v0, v1, v0
	v_cmp_ne_u32_e32 vcc, v4, v0
	v_mov_b32_e32 v4, v0
	v_mov_b64_e32 v[0:1], s[4:5]
	s_and_saveexec_b64 s[2:3], vcc
	s_cbranch_execz .LBB0_466
	v_mov_b32_e32 v0, 0
	global_load_dword v1, v0, s[4:5] offset:-4096 sc1
	s_mov_b64 s[10:11], 0
	s_waitcnt vmcnt(0)
	v_cmp_lt_u32_e32 vcc, v1, v4
	s_and_saveexec_b64 s[8:9], vcc
	s_cbranch_execz .LBB0_465
	s_add_u32 s6, s86, 0x4200
	s_addc_u32 s7, s87, 0
	s_mov_b32 s20, 1
	s_branch .LBB0_457

.LBB0_459:
	global_load_dword v1, v0, s[4:5] offset:-4096 sc1
	s_add_i32 s20, s20, 1
	s_mov_b64 s[14:15], -1
	s_waitcnt vmcnt(0)
	v_cmp_ge_u32_e32 vcc, v1, v4
	s_orn2_b64 s[18:19], vcc, exec
	s_branch .LBB0_456

.LBB0_576:
	s_or_b64 exec, exec, s[8:9]
	s_waitcnt lgkmcnt(0)
	v_cvt_f32_u32_e32 v3, v0
	s_waitcnt vmcnt(1)
	v_readfirstlane_b32 s6, v2
	s_mov_b64 s[8:9], -1
	v_rcp_iflag_f32_e32 v3, v3
	v_add_u32_e32 v1, s6, v1
	v_add_u32_e32 v4, 1, v1
	s_add_u32 s6, s4, 0x1000
	v_mul_f32_e32 v2, 0x4f7ffffe, v3
	v_cvt_u32_f32_e32 v2, v2
	v_sub_u32_e32 v3, 0, v0
	s_addc_u32 s7, s5, 0
	v_mul_lo_u32 v3, v3, v2
	v_mul_hi_u32 v3, v2, v3
	v_add_u32_e32 v2, v2, v3
	v_mul_hi_u32 v2, v1, v2
	v_mul_lo_u32 v3, v2, v0
	v_sub_u32_e32 v1, v1, v3
	v_add_u32_e32 v5, 1, v2
	v_cmp_ge_u32_e32 vcc, v1, v0
	v_sub_u32_e32 v3, v1, v0
	s_nop 0
	v_cndmask_b32_e32 v2, v2, v5, vcc
	v_cndmask_b32_e32 v1, v1, v3, vcc
	v_add_u32_e32 v3, 1, v2
	v_cmp_ge_u32_e32 vcc, v1, v0
	s_nop 1
	v_cndmask_b32_e32 v2, v2, v3, vcc
	v_mul_lo_u32 v1, v0, v2
	v_add_u32_e32 v0, v1, v0
	v_cmp_ne_u32_e32 vcc, v4, v0
	v_mov_b32_e32 v4, v0
	v_mov_b64_e32 v[0:1], s[6:7]
	s_and_saveexec_b64 s[4:5], vcc
	s_cbranch_execz .LBB0_589
	v_mov_b32_e32 v0, 0
	global_load_dword v1, v0, s[6:7] offset:-4096 sc1
	s_mov_b64 s[12:13], 0
	s_waitcnt vmcnt(0)
	v_cmp_lt_u32_e32 vcc, v1, v4
	s_and_saveexec_b64 s[10:11], vcc
	s_cbranch_execz .LBB0_588
	s_add_u32 s8, s86, 0x4200
	s_addc_u32 s9, s87, 0
	s_mov_b32 s22, 1
	s_branch .LBB0_580

.LBB0_582:
	global_load_dword v1, v0, s[6:7] offset:-4096 sc1
	s_add_i32 s22, s22, 1
	s_mov_b64 s[16:17], -1
	s_waitcnt vmcnt(0)
	v_cmp_ge_u32_e32 vcc, v1, v4
	s_orn2_b64 s[20:21], vcc, exec
	s_branch .LBB0_579

.LBB0_1355:
	s_or_b64 exec, exec, s[8:9]
	s_waitcnt lgkmcnt(0)
	v_cvt_f32_u32_e32 v3, v0
	s_waitcnt vmcnt(1)
	v_readfirstlane_b32 s6, v2
	s_mov_b64 s[8:9], -1
	v_rcp_iflag_f32_e32 v3, v3
	v_add_u32_e32 v1, s6, v1
	v_add_u32_e32 v4, 1, v1
	s_add_u32 s6, s4, 0x1000
	v_mul_f32_e32 v2, 0x4f7ffffe, v3
	v_cvt_u32_f32_e32 v2, v2
	v_sub_u32_e32 v3, 0, v0
	s_addc_u32 s7, s5, 0
	v_mul_lo_u32 v3, v3, v2
	v_mul_hi_u32 v3, v2, v3
	v_add_u32_e32 v2, v2, v3
	v_mul_hi_u32 v2, v1, v2
	v_mul_lo_u32 v3, v2, v0
	v_sub_u32_e32 v1, v1, v3
	v_add_u32_e32 v5, 1, v2
	v_cmp_ge_u32_e32 vcc, v1, v0
	v_sub_u32_e32 v3, v1, v0
	s_nop 0
	v_cndmask_b32_e32 v2, v2, v5, vcc
	v_cndmask_b32_e32 v1, v1, v3, vcc
	v_add_u32_e32 v3, 1, v2
	v_cmp_ge_u32_e32 vcc, v1, v0
	s_nop 1
	v_cndmask_b32_e32 v2, v2, v3, vcc
	v_mul_lo_u32 v1, v0, v2
	v_add_u32_e32 v0, v1, v0
	v_cmp_ne_u32_e32 vcc, v4, v0
	v_mov_b32_e32 v4, v0
	v_mov_b64_e32 v[0:1], s[6:7]
	s_and_saveexec_b64 s[4:5], vcc
	s_cbranch_execz .LBB0_1368
	v_mov_b32_e32 v0, 0
	global_load_dword v1, v0, s[6:7] offset:-4096 sc1
	s_mov_b64 s[12:13], 0
	s_waitcnt vmcnt(0)
	v_cmp_lt_u32_e32 vcc, v1, v4
	s_and_saveexec_b64 s[10:11], vcc
	s_cbranch_execz .LBB0_1367
	s_add_u32 s8, s70, 0x4200
	s_addc_u32 s9, s71, 0
	s_mov_b32 s22, 1
	s_branch .LBB0_1359

.LBB0_1497:
	s_or_b64 exec, exec, s[10:11]
	s_waitcnt lgkmcnt(0)
	v_cvt_f32_u32_e32 v3, v0
	s_waitcnt vmcnt(1)
	v_readfirstlane_b32 s8, v2
	s_mov_b64 s[10:11], -1
	v_rcp_iflag_f32_e32 v3, v3
	v_add_u32_e32 v1, s8, v1
	v_add_u32_e32 v4, 1, v1
	s_add_u32 s8, s6, 0x1000
	v_mul_f32_e32 v2, 0x4f7ffffe, v3
	v_cvt_u32_f32_e32 v2, v2
	v_sub_u32_e32 v3, 0, v0
	s_addc_u32 s9, s7, 0
	v_mul_lo_u32 v3, v3, v2
	v_mul_hi_u32 v3, v2, v3
	v_add_u32_e32 v2, v2, v3
	v_mul_hi_u32 v2, v1, v2
	v_mul_lo_u32 v3, v2, v0
	v_sub_u32_e32 v1, v1, v3
	v_add_u32_e32 v5, 1, v2
	v_cmp_ge_u32_e32 vcc, v1, v0
	v_sub_u32_e32 v3, v1, v0
	s_nop 0
	v_cndmask_b32_e32 v2, v2, v5, vcc
	v_cndmask_b32_e32 v1, v1, v3, vcc
	v_add_u32_e32 v3, 1, v2
	v_cmp_ge_u32_e32 vcc, v1, v0
	s_nop 1
	v_cndmask_b32_e32 v2, v2, v3, vcc
	v_mul_lo_u32 v1, v0, v2
	v_add_u32_e32 v0, v1, v0
	v_cmp_ne_u32_e32 vcc, v4, v0
	v_mov_b32_e32 v4, v0
	v_mov_b64_e32 v[0:1], s[8:9]
	s_and_saveexec_b64 s[6:7], vcc
	s_cbranch_execz .LBB0_1510
	v_mov_b32_e32 v0, 0
	global_load_dword v1, v0, s[8:9] offset:-4096 sc1
	s_mov_b64 s[14:15], 0
	s_waitcnt vmcnt(0)
	v_cmp_lt_u32_e32 vcc, v1, v4
	s_and_saveexec_b64 s[12:13], vcc
	s_cbranch_execz .LBB0_1509
	s_add_u32 s10, s70, 0x4200
	s_addc_u32 s11, s71, 0
	s_mov_b32 s24, 1
	s_branch .LBB0_1501

.LBB0_1503:
	global_load_dword v1, v0, s[8:9] offset:-4096 sc1
	s_add_i32 s24, s24, 1
	s_mov_b64 s[18:19], -1
	s_waitcnt vmcnt(0)
	v_cmp_ge_u32_e32 vcc, v1, v4
	s_orn2_b64 s[22:23], vcc, exec
	s_branch .LBB0_1500

.LBB0_1624:
	s_or_b64 exec, exec, s[8:9]
	s_waitcnt lgkmcnt(0)
	v_cvt_f32_u32_e32 v3, v0
	s_waitcnt vmcnt(1)
	v_readfirstlane_b32 s6, v2
	s_mov_b64 s[8:9], -1
	v_rcp_iflag_f32_e32 v3, v3
	v_add_u32_e32 v1, s6, v1
	v_add_u32_e32 v4, 1, v1
	s_add_u32 s6, s2, 0x1000
	v_mul_f32_e32 v2, 0x4f7ffffe, v3
	v_cvt_u32_f32_e32 v2, v2
	v_sub_u32_e32 v3, 0, v0
	s_addc_u32 s7, s3, 0
	v_mul_lo_u32 v3, v3, v2
	v_mul_hi_u32 v3, v2, v3
	v_add_u32_e32 v2, v2, v3
	v_mul_hi_u32 v2, v1, v2
	v_mul_lo_u32 v3, v2, v0
	v_sub_u32_e32 v1, v1, v3
	v_add_u32_e32 v5, 1, v2
	v_cmp_ge_u32_e32 vcc, v1, v0
	v_sub_u32_e32 v3, v1, v0
	s_nop 0
	v_cndmask_b32_e32 v2, v2, v5, vcc
	v_cndmask_b32_e32 v1, v1, v3, vcc
	v_add_u32_e32 v3, 1, v2
	v_cmp_ge_u32_e32 vcc, v1, v0
	s_nop 1
	v_cndmask_b32_e32 v2, v2, v3, vcc
	v_mul_lo_u32 v1, v0, v2
	v_add_u32_e32 v0, v1, v0
	v_cmp_ne_u32_e32 vcc, v4, v0
	v_mov_b32_e32 v4, v0
	v_mov_b64_e32 v[0:1], s[6:7]
	s_and_saveexec_b64 s[2:3], vcc
	s_cbranch_execz .LBB0_1637
	v_mov_b32_e32 v0, 0
	global_load_dword v1, v0, s[6:7] offset:-4096 sc1
	s_mov_b64 s[14:15], 0
	s_waitcnt vmcnt(0)
	v_cmp_lt_u32_e32 vcc, v1, v4
	s_and_saveexec_b64 s[12:13], vcc
	s_cbranch_execz .LBB0_1636
	s_add_u32 s8, s70, 0x4200
	s_addc_u32 s9, s71, 0
	s_mov_b32 s26, 1
	s_branch .LBB0_1628

.LBB0_1630:
	global_load_dword v1, v0, s[6:7] offset:-4096 sc1
	s_add_i32 s26, s26, 1
	s_mov_b64 s[20:21], -1
	s_waitcnt vmcnt(0)
	v_cmp_ge_u32_e32 vcc, v1, v4
	s_orn2_b64 s[24:25], vcc, exec
	s_branch .LBB0_1627

.LBB0_1763:
	s_or_b64 exec, exec, s[10:11]
	s_waitcnt lgkmcnt(0)
	v_cvt_f32_u32_e32 v3, v0
	s_waitcnt vmcnt(1)
	v_readfirstlane_b32 s8, v2
	s_mov_b64 s[10:11], -1
	v_rcp_iflag_f32_e32 v3, v3
	v_add_u32_e32 v1, s8, v1
	v_add_u32_e32 v4, 1, v1
	s_add_u32 s8, s6, 0x1000
	v_mul_f32_e32 v2, 0x4f7ffffe, v3
	v_cvt_u32_f32_e32 v2, v2
	v_sub_u32_e32 v3, 0, v0
	s_addc_u32 s9, s7, 0
	v_mul_lo_u32 v3, v3, v2
	v_mul_hi_u32 v3, v2, v3
	v_add_u32_e32 v2, v2, v3
	v_mul_hi_u32 v2, v1, v2
	v_mul_lo_u32 v3, v2, v0
	v_sub_u32_e32 v1, v1, v3
	v_add_u32_e32 v5, 1, v2
	v_cmp_ge_u32_e32 vcc, v1, v0
	v_sub_u32_e32 v3, v1, v0
	s_nop 0
	v_cndmask_b32_e32 v2, v2, v5, vcc
	v_cndmask_b32_e32 v1, v1, v3, vcc
	v_add_u32_e32 v3, 1, v2
	v_cmp_ge_u32_e32 vcc, v1, v0
	s_nop 1
	v_cndmask_b32_e32 v2, v2, v3, vcc
	v_mul_lo_u32 v1, v0, v2
	v_add_u32_e32 v0, v1, v0
	v_cmp_ne_u32_e32 vcc, v4, v0
	v_mov_b32_e32 v4, v0
	v_mov_b64_e32 v[0:1], s[8:9]
	s_and_saveexec_b64 s[6:7], vcc
	s_cbranch_execz .LBB0_1776
	v_mov_b32_e32 v0, 0
	global_load_dword v1, v0, s[8:9] offset:-4096 sc1
	s_mov_b64 s[14:15], 0
	s_waitcnt vmcnt(0)
	v_cmp_lt_u32_e32 vcc, v1, v4
	s_and_saveexec_b64 s[12:13], vcc
	s_cbranch_execz .LBB0_1775
	s_add_u32 s10, s70, 0x4200
	s_addc_u32 s11, s71, 0
	s_mov_b32 s26, 1
	s_branch .LBB0_1767

.LBB0_1769:
	global_load_dword v1, v0, s[8:9] offset:-4096 sc1
	s_add_i32 s26, s26, 1
	s_mov_b64 s[20:21], -1
	s_waitcnt vmcnt(0)
	v_cmp_ge_u32_e32 vcc, v1, v4
	s_orn2_b64 s[24:25], vcc, exec
	s_branch .LBB0_1766

.LBB0_1890:
	s_or_b64 exec, exec, s[10:11]
	s_waitcnt lgkmcnt(0)
	v_cvt_f32_u32_e32 v3, v0
	s_waitcnt vmcnt(1)
	v_readfirstlane_b32 s8, v2
	s_mov_b64 s[10:11], -1
	v_rcp_iflag_f32_e32 v3, v3
	v_add_u32_e32 v1, s8, v1
	v_add_u32_e32 v4, 1, v1
	s_add_u32 s8, s6, 0x1000
	v_mul_f32_e32 v2, 0x4f7ffffe, v3
	v_cvt_u32_f32_e32 v2, v2
	v_sub_u32_e32 v3, 0, v0
	s_addc_u32 s9, s7, 0
	v_mul_lo_u32 v3, v3, v2
	v_mul_hi_u32 v3, v2, v3
	v_add_u32_e32 v2, v2, v3
	v_mul_hi_u32 v2, v1, v2
	v_mul_lo_u32 v3, v2, v0
	v_sub_u32_e32 v1, v1, v3
	v_add_u32_e32 v5, 1, v2
	v_cmp_ge_u32_e32 vcc, v1, v0
	v_sub_u32_e32 v3, v1, v0
	s_nop 0
	v_cndmask_b32_e32 v2, v2, v5, vcc
	v_cndmask_b32_e32 v1, v1, v3, vcc
	v_add_u32_e32 v3, 1, v2
	v_cmp_ge_u32_e32 vcc, v1, v0
	s_nop 1
	v_cndmask_b32_e32 v2, v2, v3, vcc
	v_mul_lo_u32 v1, v0, v2
	v_add_u32_e32 v0, v1, v0
	v_cmp_ne_u32_e32 vcc, v4, v0
	v_mov_b32_e32 v4, v0
	v_mov_b64_e32 v[0:1], s[8:9]
	s_and_saveexec_b64 s[6:7], vcc
	s_cbranch_execz .LBB0_1903
	v_mov_b32_e32 v0, 0
	global_load_dword v1, v0, s[8:9] offset:-4096 sc1
	s_mov_b64 s[18:19], 0
	s_waitcnt vmcnt(0)
	v_cmp_lt_u32_e32 vcc, v1, v4
	s_and_saveexec_b64 s[14:15], vcc
	s_cbranch_execz .LBB0_1902
	s_add_u32 s10, s70, 0x4200
	s_addc_u32 s11, s71, 0
	s_mov_b32 s28, 1
	s_branch .LBB0_1894

.LBB0_1896:
	global_load_dword v1, v0, s[8:9] offset:-4096 sc1
	s_add_i32 s28, s28, 1
	s_mov_b64 s[22:23], -1
	s_waitcnt vmcnt(0)
	v_cmp_ge_u32_e32 vcc, v1, v4
	s_orn2_b64 s[26:27], vcc, exec
	s_branch .LBB0_1893

.LBB0_2053:
	s_or_b64 exec, exec, s[10:11]
	s_waitcnt lgkmcnt(0)
	v_cvt_f32_u32_e32 v3, v0
	s_waitcnt vmcnt(1)
	v_readfirstlane_b32 s8, v2
	s_mov_b64 s[10:11], -1
	v_rcp_iflag_f32_e32 v3, v3
	v_add_u32_e32 v1, s8, v1
	v_add_u32_e32 v4, 1, v1
	s_add_u32 s8, s6, 0x1000
	v_mul_f32_e32 v2, 0x4f7ffffe, v3
	v_cvt_u32_f32_e32 v2, v2
	v_sub_u32_e32 v3, 0, v0
	s_addc_u32 s9, s7, 0
	v_mul_lo_u32 v3, v3, v2
	v_mul_hi_u32 v3, v2, v3
	v_add_u32_e32 v2, v2, v3
	v_mul_hi_u32 v2, v1, v2
	v_mul_lo_u32 v3, v2, v0
	v_sub_u32_e32 v1, v1, v3
	v_add_u32_e32 v5, 1, v2
	v_cmp_ge_u32_e32 vcc, v1, v0
	v_sub_u32_e32 v3, v1, v0
	s_nop 0
	v_cndmask_b32_e32 v2, v2, v5, vcc
	v_cndmask_b32_e32 v1, v1, v3, vcc
	v_add_u32_e32 v3, 1, v2
	v_cmp_ge_u32_e32 vcc, v1, v0
	s_nop 1
	v_cndmask_b32_e32 v2, v2, v3, vcc
	v_mul_lo_u32 v1, v0, v2
	v_add_u32_e32 v0, v1, v0
	v_cmp_ne_u32_e32 vcc, v4, v0
	v_mov_b32_e32 v4, v0
	v_mov_b64_e32 v[0:1], s[8:9]
	s_and_saveexec_b64 s[6:7], vcc
	s_cbranch_execz .LBB0_2066
	v_mov_b32_e32 v0, 0
	global_load_dword v1, v0, s[8:9] offset:-4096 sc1
	s_mov_b64 s[20:21], 0
	s_waitcnt vmcnt(0)
	v_cmp_lt_u32_e32 vcc, v1, v4
	s_and_saveexec_b64 s[18:19], vcc
	s_cbranch_execz .LBB0_2065
	s_add_u32 s10, s70, 0x4200
	s_addc_u32 s11, s71, 0
	s_mov_b32 s30, 1
	s_branch .LBB0_2057

.LBB0_2059:
	global_load_dword v1, v0, s[8:9] offset:-4096 sc1
	s_add_i32 s30, s30, 1
	s_mov_b64 s[24:25], -1
	s_waitcnt vmcnt(0)
	v_cmp_ge_u32_e32 vcc, v1, v4
	s_orn2_b64 s[28:29], vcc, exec
	s_branch .LBB0_2056

.LBB0_2212:
	s_or_b64 exec, exec, s[10:11]
	s_waitcnt lgkmcnt(0)
	v_cvt_f32_u32_e32 v3, v0
	s_waitcnt vmcnt(1)
	v_readfirstlane_b32 s6, v2
	s_mov_b64 s[10:11], -1
	v_rcp_iflag_f32_e32 v3, v3
	v_add_u32_e32 v1, s6, v1
	v_add_u32_e32 v4, 1, v1
	s_add_u32 s6, s4, 0x1000
	v_mul_f32_e32 v2, 0x4f7ffffe, v3
	v_cvt_u32_f32_e32 v2, v2
	v_sub_u32_e32 v3, 0, v0
	s_addc_u32 s7, s5, 0
	v_mul_lo_u32 v3, v3, v2
	v_mul_hi_u32 v3, v2, v3
	v_add_u32_e32 v2, v2, v3
	v_mul_hi_u32 v2, v1, v2
	v_mul_lo_u32 v3, v2, v0
	v_sub_u32_e32 v1, v1, v3
	v_add_u32_e32 v5, 1, v2
	v_cmp_ge_u32_e32 vcc, v1, v0
	v_sub_u32_e32 v3, v1, v0
	s_nop 0
	v_cndmask_b32_e32 v2, v2, v5, vcc
	v_cndmask_b32_e32 v1, v1, v3, vcc
	v_add_u32_e32 v3, 1, v2
	v_cmp_ge_u32_e32 vcc, v1, v0
	s_nop 1
	v_cndmask_b32_e32 v2, v2, v3, vcc
	v_mul_lo_u32 v1, v0, v2
	v_add_u32_e32 v0, v1, v0
	v_cmp_ne_u32_e32 vcc, v4, v0
	v_mov_b32_e32 v4, v0
	v_mov_b64_e32 v[0:1], s[6:7]
	s_and_saveexec_b64 s[4:5], vcc
	s_cbranch_execz .LBB0_2225
	v_mov_b32_e32 v0, 0
	global_load_dword v1, v0, s[6:7] offset:-4096 sc1
	s_mov_b64 s[16:17], 0
	s_waitcnt vmcnt(0)
	v_cmp_lt_u32_e32 vcc, v1, v4
	s_and_saveexec_b64 s[12:13], vcc
	s_cbranch_execz .LBB0_2224
	s_add_u32 s10, s70, 0x4200
	s_addc_u32 s11, s71, 0
	s_mov_b32 s26, 1
	s_branch .LBB0_2216
